# QK-norm GEMM epilogue: rstd computed once per (row, head) by one thread each into an LDS table (one extra workgroup barrier) instead of 16 times per lane; on top of the diff-attention epilogue rewrite
# speedup vs baseline: 1.0053x; 1.0053x over previous
.LBB0_300:
	s_or_b64 exec, exec, s[4:5]
	s_waitcnt lgkmcnt(0)
	s_barrier
	v_mbcnt_lo_u32_b32 v169, -1, 0
	v_mbcnt_hi_u32_b32 v169, -1, v169
	v_readlane_b32 s8, v255, 11
	s_nop 3
	v_add_u32_e32 v169, s8, v169
	v_lshlrev_b32_e32 v168, 4, v169
	v_add_u32_e32 v168, 0x20400, v168
	ds_read_b128 v[176:179], v168
	v_lshlrev_b32_e32 v169, 2, v169
	v_add_u32_e32 v169, 0x22400, v169
	s_waitcnt lgkmcnt(0)
	v_add_f32_e32 v168, v177, v176
	v_add_f32_e32 v174, v178, v179
	v_add_f32_e32 v168, v168, v174
	v_fmamk_f32 v168, v168, 0x3c000000, v238
	v_mul_f32_e32 v174, 0x4f800000, v168
	v_cmp_gt_f32_e32 vcc, s24, v168
	s_nop 1
	v_cndmask_b32_e32 v168, v168, v174, vcc
	v_sqrt_f32_e32 v174, v168
	s_nop 0
	v_add_u32_e32 v176, -1, v174
	v_add_u32_e32 v177, 1, v174
	v_fma_f32 v178, -v176, v174, v168
	v_fma_f32 v179, -v177, v174, v168
	v_cmp_ge_f32_e64 s[8:9], 0, v178
	s_nop 1
	v_cndmask_b32_e64 v174, v174, v176, s[8:9]
	v_cmp_lt_f32_e64 s[8:9], 0, v179
	s_nop 1
	v_cndmask_b32_e64 v174, v174, v177, s[8:9]
	v_mul_f32_e32 v176, 0x37800000, v174
	v_cndmask_b32_e32 v174, v174, v176, vcc
	v_cmp_class_f32_e32 vcc, v168, v239
	s_nop 1
	v_cndmask_b32_e32 v168, v174, v168, vcc
	v_div_scale_f32 v174, s[8:9], v168, v168, 1.0
	v_rcp_f32_e32 v176, v174
	s_nop 0
	v_fma_f32 v177, -v174, v176, 1.0
	v_fmac_f32_e32 v176, v177, v176
	v_div_scale_f32 v177, vcc, 1.0, v168, 1.0
	v_mul_f32_e32 v178, v177, v176
	v_fma_f32 v179, -v174, v178, v177
	v_fmac_f32_e32 v178, v179, v176
	v_fma_f32 v174, -v174, v178, v177
	v_div_fmas_f32 v174, v174, v176, v178
	v_div_fixup_f32 v168, v174, v168, 1.0
	ds_write_b32 v169, v168
	s_waitcnt lgkmcnt(0)
	s_barrier
	v_cmp_gt_i32_e64 s[4:5], 2, v0
	v_add_u32_e32 v168, s77, v173
	v_cndmask_b32_e64 v0, 0, 1, s[72:73]
	v_and_b32_e32 v174, 8, v150
	v_cmp_ne_u32_e64 s[6:7], 1, v0
	s_andn2_b64 vcc, exec, s[72:73]
	v_ashrrev_i32_e32 v169, 31, v168
	s_cbranch_vccz .LBB0_302
	v_mov_b32_e32 v164, 0
	v_mov_b32_e32 v154, 1.0
	v_mov_b32_e32 v155, v154
	v_mov_b32_e32 v156, v154
	v_mov_b32_e32 v157, v154
	v_mov_b32_e32 v150, v154
	v_mov_b32_e32 v151, v154
	v_mov_b32_e32 v152, v154
	s_waitcnt lgkmcnt(0)
	v_mov_b32_e32 v153, v154
	v_mov_b32_e32 v165, v164
	v_mov_b32_e32 v166, v164
	v_mov_b32_e32 v167, v164
	v_mov_b32_e32 v162, v164
	v_mov_b32_e32 v163, v164
	v_mov_b32_e32 v160, v164
	v_mov_b32_e32 v161, v164
	s_branch .LBB0_303

.LBB0_303:
	v_lshrrev_b32_e32 v176, 2, v175
	v_add_u32_e32 v176, 0x1a300, v176
	ds_read_b32 v176, v176
	s_waitcnt lgkmcnt(0)
	v_mov_b32_e32 v0, v176
	v_pk_mul_f32 v[170:171], v[146:147], v[0:1] op_sel_hi:[1,0]
	v_pk_mul_f32 v[146:147], v[148:149], v[0:1] op_sel_hi:[1,0]
	v_pk_mul_f32 v[142:143], v[142:143], v[0:1] op_sel_hi:[1,0]
	v_pk_mul_f32 v[144:145], v[144:145], v[0:1] op_sel_hi:[1,0]
	s_waitcnt vmcnt(0)
	v_pk_mul_f32 v[146:147], v[68:69], v[146:147]
	v_pk_mul_f32 v[148:149], v[66:67], v[170:171]
	v_pk_mul_f32 v[144:145], v[64:65], v[144:145]
	s_and_b64 vcc, exec, s[6:7]
	v_pk_mul_f32 v[170:171], v[62:63], v[142:143]
	s_cbranch_vccnz .LBB0_305
	ds_bpermute_b32 v142, v172, v148
	ds_bpermute_b32 v143, v172, v149
	ds_bpermute_b32 v176, v172, v170
	ds_bpermute_b32 v178, v172, v146
	ds_bpermute_b32 v179, v172, v147
	ds_bpermute_b32 v177, v172, v171
	ds_bpermute_b32 v180, v172, v144
	ds_bpermute_b32 v181, v172, v145
	s_waitcnt lgkmcnt(6)
	v_pk_mul_f32 v[142:143], v[164:165], v[142:143]
	s_waitcnt lgkmcnt(3)
	v_pk_mul_f32 v[178:179], v[166:167], v[178:179]
	v_pk_fma_f32 v[148:149], v[154:155], v[148:149], v[142:143]
	s_waitcnt lgkmcnt(2)
	v_pk_mul_f32 v[142:143], v[162:163], v[176:177]
	s_waitcnt lgkmcnt(0)
	v_pk_mul_f32 v[176:177], v[160:161], v[180:181]
	v_pk_fma_f32 v[146:147], v[156:157], v[146:147], v[178:179]
	v_pk_fma_f32 v[144:145], v[152:153], v[144:145], v[176:177]
	v_pk_fma_f32 v[170:171], v[150:151], v[170:171], v[142:143]
.LBB0_305:
	v_mad_u64_u32 v[142:143], s[8:9], v168, s20, 0
	v_mov_b32_e32 v0, v143
	v_mad_u64_u32 v[168:169], s[8:9], v169, s20, v[0:1]
	v_mov_b32_e32 v143, v168
	v_cvt_pk_bf16_f32 v168, v148, v149
	v_cvt_pk_bf16_f32 v169, v146, v147
	v_cvt_pk_bf16_f32 v170, v170, v171
	v_cvt_pk_bf16_f32 v171, v144, v145
	v_lshrrev_b32_e32 v144, 2, v175
	v_add_u32_e32 v144, 0x1a300, v144
	ds_read_b32 v144, v144 offset:4
	v_lshl_add_u64 v[142:143], v[142:143], 1, s[56:57]
	v_lshl_add_u64 v[142:143], v[158:159], 1, v[142:143]
	global_store_dwordx4 v[142:143], v[168:171], off
	s_waitcnt lgkmcnt(0)
	v_mov_b32_e32 v0, v144
	v_pk_mul_f32 v[144:145], v[138:139], v[0:1] op_sel_hi:[1,0]
	v_pk_mul_f32 v[138:139], v[140:141], v[0:1] op_sel_hi:[1,0]
	v_pk_mul_f32 v[140:141], v[58:59], v[144:145]
	v_pk_mul_f32 v[144:145], v[134:135], v[0:1] op_sel_hi:[1,0]
	v_pk_mul_f32 v[134:135], v[136:137], v[0:1] op_sel_hi:[1,0]
	v_pk_mul_f32 v[138:139], v[60:61], v[138:139]
	v_pk_mul_f32 v[134:135], v[56:57], v[134:135]
	v_pk_mul_f32 v[136:137], v[54:55], v[144:145]
	s_and_b64 vcc, exec, s[6:7]
	s_cbranch_vccnz .LBB0_307
	ds_bpermute_b32 v144, v172, v140
	ds_bpermute_b32 v145, v172, v141
	ds_bpermute_b32 v146, v172, v136
	ds_bpermute_b32 v148, v172, v138
	ds_bpermute_b32 v149, v172, v139
	ds_bpermute_b32 v147, v172, v137
	ds_bpermute_b32 v168, v172, v134
	ds_bpermute_b32 v169, v172, v135
	s_waitcnt lgkmcnt(6)
	v_pk_mul_f32 v[144:145], v[164:165], v[144:145]
	s_waitcnt lgkmcnt(3)
	v_pk_mul_f32 v[148:149], v[166:167], v[148:149]
	v_pk_fma_f32 v[140:141], v[154:155], v[140:141], v[144:145]
	s_waitcnt lgkmcnt(2)
	v_pk_mul_f32 v[144:145], v[162:163], v[146:147]
	s_waitcnt lgkmcnt(0)
	v_pk_mul_f32 v[146:147], v[160:161], v[168:169]
	v_pk_fma_f32 v[138:139], v[156:157], v[138:139], v[148:149]
	v_pk_fma_f32 v[134:135], v[152:153], v[134:135], v[146:147]
	v_pk_fma_f32 v[136:137], v[150:151], v[136:137], v[144:145]

.LBB0_310:
	v_lshlrev_b32_e32 v0, 5, v152
	v_add_u32_e32 v152, 0, v0
	v_add_u32_e32 v152, 0x20400, v152
	v_lshrrev_b32_e32 v152, 2, v152
	v_add_u32_e32 v152, 0x1a300, v152
	ds_read_b32 v152, v152
	s_waitcnt lgkmcnt(0)
	s_nop 0
	v_pk_mul_f32 v[154:155], v[130:131], v[152:153] op_sel_hi:[1,0]
	v_pk_mul_f32 v[130:131], v[132:133], v[152:153] op_sel_hi:[1,0]
	v_pk_mul_f32 v[126:127], v[126:127], v[152:153] op_sel_hi:[1,0]
	v_pk_mul_f32 v[128:129], v[128:129], v[152:153] op_sel_hi:[1,0]
	v_pk_mul_f32 v[130:131], v[68:69], v[130:131]
	v_pk_mul_f32 v[132:133], v[66:67], v[154:155]
	v_pk_mul_f32 v[128:129], v[64:65], v[128:129]
	s_and_b64 vcc, exec, s[6:7]
	v_pk_mul_f32 v[152:153], v[62:63], v[126:127]
	s_cbranch_vccnz .LBB0_312
	ds_bpermute_b32 v126, v172, v132
	ds_bpermute_b32 v127, v172, v133
	ds_bpermute_b32 v154, v172, v152
	ds_bpermute_b32 v156, v172, v130
	ds_bpermute_b32 v157, v172, v131
	ds_bpermute_b32 v155, v172, v153
	ds_bpermute_b32 v160, v172, v128
	ds_bpermute_b32 v161, v172, v129
	s_waitcnt lgkmcnt(6)
	v_pk_mul_f32 v[126:127], v[146:147], v[126:127]
	s_waitcnt lgkmcnt(3)
	v_pk_mul_f32 v[156:157], v[148:149], v[156:157]
	s_waitcnt vmcnt(1)
	v_pk_fma_f32 v[132:133], v[138:139], v[132:133], v[126:127]
	s_waitcnt lgkmcnt(2)
	v_pk_mul_f32 v[126:127], v[144:145], v[154:155]
	s_waitcnt lgkmcnt(0)
	v_pk_mul_f32 v[154:155], v[142:143], v[160:161]
	v_pk_fma_f32 v[130:131], v[140:141], v[130:131], v[156:157]
	s_waitcnt vmcnt(0)
	v_pk_fma_f32 v[128:129], v[136:137], v[128:129], v[154:155]
	v_pk_fma_f32 v[152:153], v[134:135], v[152:153], v[126:127]
.LBB0_312:
	v_mad_u64_u32 v[126:127], s[8:9], v150, s20, 0
	v_mov_b32_e32 v150, v127
	v_mad_u64_u32 v[150:151], s[8:9], v151, s20, v[150:151]
	v_add_u32_e32 v0, s33, v0
	v_mov_b32_e32 v127, v150
	v_cvt_pk_bf16_f32 v150, v132, v133
	v_cvt_pk_bf16_f32 v151, v130, v131
	v_cvt_pk_bf16_f32 v152, v152, v153
	v_cvt_pk_bf16_f32 v153, v128, v129
	v_lshrrev_b32_e32 v128, 2, v0
	v_add_u32_e32 v128, 0x1a300, v128
	ds_read_b32 v128, v128 offset:4
	v_lshl_add_u64 v[126:127], v[126:127], 1, s[56:57]
	v_lshl_add_u64 v[126:127], v[158:159], 1, v[126:127]
	global_store_dwordx4 v[126:127], v[150:153], off
	s_waitcnt lgkmcnt(0)
	v_mov_b32_e32 v0, v128
	v_pk_mul_f32 v[128:129], v[122:123], v[0:1] op_sel_hi:[1,0]
	v_pk_mul_f32 v[122:123], v[124:125], v[0:1] op_sel_hi:[1,0]
	v_pk_mul_f32 v[124:125], v[58:59], v[128:129]
	v_pk_mul_f32 v[128:129], v[118:119], v[0:1] op_sel_hi:[1,0]
	v_pk_mul_f32 v[118:119], v[120:121], v[0:1] op_sel_hi:[1,0]
	v_pk_mul_f32 v[122:123], v[60:61], v[122:123]
	v_pk_mul_f32 v[118:119], v[56:57], v[118:119]
	v_pk_mul_f32 v[120:121], v[54:55], v[128:129]
	s_and_b64 vcc, exec, s[6:7]
	s_cbranch_vccnz .LBB0_314
	ds_bpermute_b32 v128, v172, v124
	ds_bpermute_b32 v129, v172, v125
	ds_bpermute_b32 v130, v172, v120
	ds_bpermute_b32 v132, v172, v122
	ds_bpermute_b32 v133, v172, v123
	ds_bpermute_b32 v131, v172, v121
	ds_bpermute_b32 v150, v172, v118
	ds_bpermute_b32 v151, v172, v119
	s_waitcnt lgkmcnt(6)
	v_pk_mul_f32 v[128:129], v[146:147], v[128:129]
	s_waitcnt lgkmcnt(3)
	v_pk_mul_f32 v[132:133], v[148:149], v[132:133]
	s_waitcnt vmcnt(2)
	v_pk_fma_f32 v[124:125], v[138:139], v[124:125], v[128:129]
	s_waitcnt lgkmcnt(2)
	v_pk_mul_f32 v[128:129], v[144:145], v[130:131]
	s_waitcnt lgkmcnt(0)
	v_pk_mul_f32 v[130:131], v[142:143], v[150:151]
	v_pk_fma_f32 v[122:123], v[140:141], v[122:123], v[132:133]
	s_waitcnt vmcnt(1)
	v_pk_fma_f32 v[118:119], v[136:137], v[118:119], v[130:131]
	v_pk_fma_f32 v[120:121], v[134:135], v[120:121], v[128:129]

.LBB0_317:
	v_lshlrev_b32_e32 v0, 5, v136
	v_add_u32_e32 v136, 0, v0
	v_add_u32_e32 v136, 0x20400, v136
	v_lshrrev_b32_e32 v136, 2, v136
	v_add_u32_e32 v136, 0x1a300, v136
	ds_read_b32 v136, v136
	s_waitcnt lgkmcnt(0)
	s_nop 0
	v_pk_mul_f32 v[138:139], v[114:115], v[136:137] op_sel_hi:[1,0]
	v_pk_mul_f32 v[114:115], v[116:117], v[136:137] op_sel_hi:[1,0]
	v_pk_mul_f32 v[110:111], v[110:111], v[136:137] op_sel_hi:[1,0]
	v_pk_mul_f32 v[112:113], v[112:113], v[136:137] op_sel_hi:[1,0]
	v_pk_mul_f32 v[114:115], v[68:69], v[114:115]
	v_pk_mul_f32 v[116:117], v[66:67], v[138:139]
	v_pk_mul_f32 v[112:113], v[64:65], v[112:113]
	s_and_b64 vcc, exec, s[6:7]
	v_pk_mul_f32 v[136:137], v[62:63], v[110:111]
	s_cbranch_vccnz .LBB0_319
	ds_bpermute_b32 v110, v172, v116
	ds_bpermute_b32 v111, v172, v117
	ds_bpermute_b32 v138, v172, v136
	ds_bpermute_b32 v140, v172, v114
	ds_bpermute_b32 v141, v172, v115
	ds_bpermute_b32 v139, v172, v137
	ds_bpermute_b32 v142, v172, v112
	ds_bpermute_b32 v143, v172, v113
	s_waitcnt lgkmcnt(6)
	v_pk_mul_f32 v[110:111], v[130:131], v[110:111]
	s_waitcnt lgkmcnt(3)
	v_pk_mul_f32 v[140:141], v[132:133], v[140:141]
	s_waitcnt vmcnt(1)
	v_pk_fma_f32 v[116:117], v[122:123], v[116:117], v[110:111]
	s_waitcnt lgkmcnt(2)
	v_pk_mul_f32 v[110:111], v[128:129], v[138:139]
	s_waitcnt lgkmcnt(0)
	v_pk_mul_f32 v[138:139], v[126:127], v[142:143]
	v_pk_fma_f32 v[114:115], v[124:125], v[114:115], v[140:141]
	s_waitcnt vmcnt(0)
	v_pk_fma_f32 v[112:113], v[120:121], v[112:113], v[138:139]
	v_pk_fma_f32 v[136:137], v[118:119], v[136:137], v[110:111]
.LBB0_319:
	v_mad_u64_u32 v[110:111], s[8:9], v134, s20, 0
	v_mov_b32_e32 v134, v111
	v_mad_u64_u32 v[134:135], s[8:9], v135, s20, v[134:135]
	v_add_u32_e32 v0, s33, v0
	v_mov_b32_e32 v111, v134
	v_cvt_pk_bf16_f32 v134, v116, v117
	v_cvt_pk_bf16_f32 v135, v114, v115
	v_cvt_pk_bf16_f32 v136, v136, v137
	v_cvt_pk_bf16_f32 v137, v112, v113
	v_lshrrev_b32_e32 v112, 2, v0
	v_add_u32_e32 v112, 0x1a300, v112
	ds_read_b32 v112, v112 offset:4
	v_lshl_add_u64 v[110:111], v[110:111], 1, s[56:57]
	v_lshl_add_u64 v[110:111], v[158:159], 1, v[110:111]
	global_store_dwordx4 v[110:111], v[134:137], off
	s_waitcnt lgkmcnt(0)
	v_mov_b32_e32 v0, v112
	v_pk_mul_f32 v[112:113], v[106:107], v[0:1] op_sel_hi:[1,0]
	v_pk_mul_f32 v[106:107], v[108:109], v[0:1] op_sel_hi:[1,0]
	v_pk_mul_f32 v[108:109], v[58:59], v[112:113]
	v_pk_mul_f32 v[112:113], v[102:103], v[0:1] op_sel_hi:[1,0]
	v_pk_mul_f32 v[102:103], v[104:105], v[0:1] op_sel_hi:[1,0]
	v_pk_mul_f32 v[106:107], v[60:61], v[106:107]
	v_pk_mul_f32 v[102:103], v[56:57], v[102:103]
	v_pk_mul_f32 v[104:105], v[54:55], v[112:113]
	s_and_b64 vcc, exec, s[6:7]
	s_cbranch_vccnz .LBB0_321
	ds_bpermute_b32 v112, v172, v108
	ds_bpermute_b32 v113, v172, v109
	ds_bpermute_b32 v114, v172, v104
	ds_bpermute_b32 v116, v172, v106
	ds_bpermute_b32 v117, v172, v107
	ds_bpermute_b32 v115, v172, v105
	ds_bpermute_b32 v134, v172, v102
	ds_bpermute_b32 v135, v172, v103
	s_waitcnt lgkmcnt(6)
	v_pk_mul_f32 v[112:113], v[130:131], v[112:113]
	s_waitcnt lgkmcnt(3)
	v_pk_mul_f32 v[116:117], v[132:133], v[116:117]
	s_waitcnt vmcnt(2)
	v_pk_fma_f32 v[108:109], v[122:123], v[108:109], v[112:113]
	s_waitcnt lgkmcnt(2)
	v_pk_mul_f32 v[112:113], v[128:129], v[114:115]
	s_waitcnt lgkmcnt(0)
	v_pk_mul_f32 v[114:115], v[126:127], v[134:135]
	v_pk_fma_f32 v[106:107], v[124:125], v[106:107], v[116:117]
	s_waitcnt vmcnt(1)
	v_pk_fma_f32 v[102:103], v[120:121], v[102:103], v[114:115]
	v_pk_fma_f32 v[104:105], v[118:119], v[104:105], v[112:113]

.LBB0_324:
	v_lshlrev_b32_e32 v0, 5, v120
	v_add_u32_e32 v120, 0, v0
	v_add_u32_e32 v120, 0x20400, v120
	v_lshrrev_b32_e32 v120, 2, v120
	v_add_u32_e32 v120, 0x1a300, v120
	ds_read_b32 v120, v120
	s_waitcnt lgkmcnt(0)
	s_nop 0
	v_pk_mul_f32 v[122:123], v[98:99], v[120:121] op_sel_hi:[1,0]
	v_pk_mul_f32 v[98:99], v[100:101], v[120:121] op_sel_hi:[1,0]
	v_pk_mul_f32 v[94:95], v[94:95], v[120:121] op_sel_hi:[1,0]
	v_pk_mul_f32 v[96:97], v[96:97], v[120:121] op_sel_hi:[1,0]
	v_pk_mul_f32 v[98:99], v[68:69], v[98:99]
	v_pk_mul_f32 v[100:101], v[66:67], v[122:123]
	v_pk_mul_f32 v[96:97], v[64:65], v[96:97]
	s_and_b64 vcc, exec, s[6:7]
	v_pk_mul_f32 v[120:121], v[62:63], v[94:95]
	s_cbranch_vccnz .LBB0_326
	ds_bpermute_b32 v94, v172, v100
	ds_bpermute_b32 v95, v172, v101
	ds_bpermute_b32 v122, v172, v120
	ds_bpermute_b32 v124, v172, v98
	ds_bpermute_b32 v125, v172, v99
	ds_bpermute_b32 v123, v172, v121
	ds_bpermute_b32 v126, v172, v96
	ds_bpermute_b32 v127, v172, v97
	s_waitcnt lgkmcnt(6)
	v_pk_mul_f32 v[94:95], v[114:115], v[94:95]
	s_waitcnt lgkmcnt(3)
	v_pk_mul_f32 v[124:125], v[116:117], v[124:125]
	s_waitcnt vmcnt(1)
	v_pk_fma_f32 v[100:101], v[106:107], v[100:101], v[94:95]
	s_waitcnt lgkmcnt(2)
	v_pk_mul_f32 v[94:95], v[112:113], v[122:123]
	s_waitcnt lgkmcnt(0)
	v_pk_mul_f32 v[122:123], v[110:111], v[126:127]
	v_pk_fma_f32 v[98:99], v[108:109], v[98:99], v[124:125]
	s_waitcnt vmcnt(0)
	v_pk_fma_f32 v[96:97], v[104:105], v[96:97], v[122:123]
	v_pk_fma_f32 v[120:121], v[102:103], v[120:121], v[94:95]
.LBB0_326:
	v_mad_u64_u32 v[94:95], s[8:9], v118, s20, 0
	v_mov_b32_e32 v118, v95
	v_mad_u64_u32 v[118:119], s[8:9], v119, s20, v[118:119]
	v_add_u32_e32 v0, s33, v0
	v_mov_b32_e32 v95, v118
	v_cvt_pk_bf16_f32 v118, v100, v101
	v_cvt_pk_bf16_f32 v119, v98, v99
	v_cvt_pk_bf16_f32 v120, v120, v121
	v_cvt_pk_bf16_f32 v121, v96, v97
	v_lshrrev_b32_e32 v96, 2, v0
	v_add_u32_e32 v96, 0x1a300, v96
	ds_read_b32 v96, v96 offset:4
	v_lshl_add_u64 v[94:95], v[94:95], 1, s[56:57]
	v_lshl_add_u64 v[94:95], v[158:159], 1, v[94:95]
	global_store_dwordx4 v[94:95], v[118:121], off
	s_waitcnt lgkmcnt(0)
	v_mov_b32_e32 v0, v96
	v_pk_mul_f32 v[96:97], v[90:91], v[0:1] op_sel_hi:[1,0]
	v_pk_mul_f32 v[90:91], v[92:93], v[0:1] op_sel_hi:[1,0]
	v_pk_mul_f32 v[92:93], v[58:59], v[96:97]
	v_pk_mul_f32 v[96:97], v[86:87], v[0:1] op_sel_hi:[1,0]
	v_pk_mul_f32 v[86:87], v[88:89], v[0:1] op_sel_hi:[1,0]
	v_pk_mul_f32 v[90:91], v[60:61], v[90:91]
	v_pk_mul_f32 v[86:87], v[56:57], v[86:87]
	v_pk_mul_f32 v[88:89], v[54:55], v[96:97]
	s_and_b64 vcc, exec, s[6:7]
	s_cbranch_vccnz .LBB0_328
	ds_bpermute_b32 v96, v172, v92
	ds_bpermute_b32 v97, v172, v93
	ds_bpermute_b32 v98, v172, v88
	ds_bpermute_b32 v100, v172, v90
	ds_bpermute_b32 v101, v172, v91
	ds_bpermute_b32 v99, v172, v89
	ds_bpermute_b32 v118, v172, v86
	ds_bpermute_b32 v119, v172, v87
	s_waitcnt lgkmcnt(6)
	v_pk_mul_f32 v[96:97], v[114:115], v[96:97]
	s_waitcnt lgkmcnt(3)
	v_pk_mul_f32 v[100:101], v[116:117], v[100:101]
	s_waitcnt vmcnt(2)
	v_pk_fma_f32 v[92:93], v[106:107], v[92:93], v[96:97]
	s_waitcnt lgkmcnt(2)
	v_pk_mul_f32 v[96:97], v[112:113], v[98:99]
	s_waitcnt lgkmcnt(0)
	v_pk_mul_f32 v[98:99], v[110:111], v[118:119]
	v_pk_fma_f32 v[90:91], v[108:109], v[90:91], v[100:101]
	s_waitcnt vmcnt(1)
	v_pk_fma_f32 v[86:87], v[104:105], v[86:87], v[98:99]
	v_pk_fma_f32 v[88:89], v[102:103], v[88:89], v[96:97]

.LBB0_331:
	v_lshlrev_b32_e32 v0, 5, v104
	v_add_u32_e32 v104, 0, v0
	v_add_u32_e32 v104, 0x20400, v104
	v_lshrrev_b32_e32 v104, 2, v104
	v_add_u32_e32 v104, 0x1a300, v104
	ds_read_b32 v104, v104
	s_waitcnt lgkmcnt(0)
	s_nop 0
	v_pk_mul_f32 v[106:107], v[82:83], v[104:105] op_sel_hi:[1,0]
	v_pk_mul_f32 v[82:83], v[84:85], v[104:105] op_sel_hi:[1,0]
	v_pk_mul_f32 v[78:79], v[78:79], v[104:105] op_sel_hi:[1,0]
	v_pk_mul_f32 v[80:81], v[80:81], v[104:105] op_sel_hi:[1,0]
	v_pk_mul_f32 v[82:83], v[68:69], v[82:83]
	v_pk_mul_f32 v[84:85], v[66:67], v[106:107]
	v_pk_mul_f32 v[80:81], v[64:65], v[80:81]
	s_and_b64 vcc, exec, s[6:7]
	v_pk_mul_f32 v[104:105], v[62:63], v[78:79]
	s_cbranch_vccnz .LBB0_333
	ds_bpermute_b32 v78, v172, v84
	ds_bpermute_b32 v79, v172, v85
	ds_bpermute_b32 v106, v172, v104
	ds_bpermute_b32 v108, v172, v82
	ds_bpermute_b32 v109, v172, v83
	ds_bpermute_b32 v107, v172, v105
	ds_bpermute_b32 v110, v172, v80
	ds_bpermute_b32 v111, v172, v81
	s_waitcnt lgkmcnt(6)
	v_pk_mul_f32 v[78:79], v[98:99], v[78:79]
	s_waitcnt lgkmcnt(3)
	v_pk_mul_f32 v[108:109], v[100:101], v[108:109]
	s_waitcnt vmcnt(1)
	v_pk_fma_f32 v[84:85], v[90:91], v[84:85], v[78:79]
	s_waitcnt lgkmcnt(2)
	v_pk_mul_f32 v[78:79], v[96:97], v[106:107]
	s_waitcnt lgkmcnt(0)
	v_pk_mul_f32 v[106:107], v[94:95], v[110:111]
	v_pk_fma_f32 v[82:83], v[92:93], v[82:83], v[108:109]
	s_waitcnt vmcnt(0)
	v_pk_fma_f32 v[80:81], v[88:89], v[80:81], v[106:107]
	v_pk_fma_f32 v[104:105], v[86:87], v[104:105], v[78:79]
.LBB0_333:
	v_mad_u64_u32 v[78:79], s[8:9], v102, s20, 0
	v_mov_b32_e32 v102, v79
	v_mad_u64_u32 v[102:103], s[8:9], v103, s20, v[102:103]
	v_add_u32_e32 v0, s33, v0
	v_mov_b32_e32 v79, v102
	v_cvt_pk_bf16_f32 v102, v84, v85
	v_cvt_pk_bf16_f32 v103, v82, v83
	v_cvt_pk_bf16_f32 v104, v104, v105
	v_cvt_pk_bf16_f32 v105, v80, v81
	v_lshrrev_b32_e32 v80, 2, v0
	v_add_u32_e32 v80, 0x1a300, v80
	ds_read_b32 v80, v80 offset:4
	v_lshl_add_u64 v[78:79], v[78:79], 1, s[56:57]
	v_lshl_add_u64 v[78:79], v[158:159], 1, v[78:79]
	global_store_dwordx4 v[78:79], v[102:105], off
	s_waitcnt lgkmcnt(0)
	v_mov_b32_e32 v0, v80
	v_pk_mul_f32 v[80:81], v[74:75], v[0:1] op_sel_hi:[1,0]
	v_pk_mul_f32 v[74:75], v[76:77], v[0:1] op_sel_hi:[1,0]
	v_pk_mul_f32 v[76:77], v[58:59], v[80:81]
	v_pk_mul_f32 v[80:81], v[70:71], v[0:1] op_sel_hi:[1,0]
	v_pk_mul_f32 v[70:71], v[72:73], v[0:1] op_sel_hi:[1,0]
	v_pk_mul_f32 v[74:75], v[60:61], v[74:75]
	v_pk_mul_f32 v[70:71], v[56:57], v[70:71]
	v_pk_mul_f32 v[72:73], v[54:55], v[80:81]
	s_and_b64 vcc, exec, s[6:7]
	s_cbranch_vccnz .LBB0_335
	ds_bpermute_b32 v80, v172, v76
	ds_bpermute_b32 v81, v172, v77
	ds_bpermute_b32 v82, v172, v72
	ds_bpermute_b32 v84, v172, v74
	ds_bpermute_b32 v85, v172, v75
	ds_bpermute_b32 v83, v172, v73
	ds_bpermute_b32 v102, v172, v70
	ds_bpermute_b32 v103, v172, v71
	s_waitcnt lgkmcnt(6)
	v_pk_mul_f32 v[80:81], v[98:99], v[80:81]
	s_waitcnt lgkmcnt(3)
	v_pk_mul_f32 v[84:85], v[100:101], v[84:85]
	s_waitcnt vmcnt(2)
	v_pk_fma_f32 v[76:77], v[90:91], v[76:77], v[80:81]
	s_waitcnt lgkmcnt(2)
	v_pk_mul_f32 v[80:81], v[96:97], v[82:83]
	s_waitcnt lgkmcnt(0)
	v_pk_mul_f32 v[82:83], v[94:95], v[102:103]
	v_pk_fma_f32 v[74:75], v[92:93], v[74:75], v[84:85]
	s_waitcnt vmcnt(1)
	v_pk_fma_f32 v[70:71], v[88:89], v[70:71], v[82:83]
	v_pk_fma_f32 v[72:73], v[86:87], v[72:73], v[80:81]

.LBB0_338:
	v_lshlrev_b32_e32 v0, 5, v88
	v_add_u32_e32 v88, 0, v0
	v_add_u32_e32 v88, 0x20400, v88
	v_lshrrev_b32_e32 v88, 2, v88
	v_add_u32_e32 v88, 0x1a300, v88
	ds_read_b32 v88, v88
	s_waitcnt lgkmcnt(0)
	s_nop 0
	v_pk_mul_f32 v[90:91], v[50:51], v[88:89] op_sel_hi:[1,0]
	v_pk_mul_f32 v[50:51], v[52:53], v[88:89] op_sel_hi:[1,0]
	v_pk_mul_f32 v[46:47], v[46:47], v[88:89] op_sel_hi:[1,0]
	v_pk_mul_f32 v[48:49], v[48:49], v[88:89] op_sel_hi:[1,0]
	v_pk_mul_f32 v[50:51], v[68:69], v[50:51]
	v_pk_mul_f32 v[52:53], v[66:67], v[90:91]
	v_pk_mul_f32 v[48:49], v[64:65], v[48:49]
	s_and_b64 vcc, exec, s[6:7]
	v_pk_mul_f32 v[88:89], v[62:63], v[46:47]
	s_cbranch_vccnz .LBB0_340
	ds_bpermute_b32 v46, v172, v52
	ds_bpermute_b32 v47, v172, v53
	ds_bpermute_b32 v90, v172, v88
	ds_bpermute_b32 v92, v172, v50
	ds_bpermute_b32 v93, v172, v51
	ds_bpermute_b32 v91, v172, v89
	ds_bpermute_b32 v94, v172, v48
	ds_bpermute_b32 v95, v172, v49
	s_waitcnt lgkmcnt(6)
	v_pk_mul_f32 v[46:47], v[82:83], v[46:47]
	s_waitcnt lgkmcnt(3)
	v_pk_mul_f32 v[92:93], v[84:85], v[92:93]
	s_waitcnt vmcnt(1)
	v_pk_fma_f32 v[52:53], v[74:75], v[52:53], v[46:47]
	s_waitcnt lgkmcnt(2)
	v_pk_mul_f32 v[46:47], v[80:81], v[90:91]
	s_waitcnt lgkmcnt(0)
	v_pk_mul_f32 v[90:91], v[78:79], v[94:95]
	v_pk_fma_f32 v[50:51], v[76:77], v[50:51], v[92:93]
	s_waitcnt vmcnt(0)
	v_pk_fma_f32 v[48:49], v[72:73], v[48:49], v[90:91]
	v_pk_fma_f32 v[88:89], v[70:71], v[88:89], v[46:47]
.LBB0_340:
	v_mad_u64_u32 v[46:47], s[8:9], v86, s20, 0
	v_mov_b32_e32 v86, v47
	v_mad_u64_u32 v[86:87], s[8:9], v87, s20, v[86:87]
	v_add_u32_e32 v0, s33, v0
	v_mov_b32_e32 v47, v86
	v_cvt_pk_bf16_f32 v86, v52, v53
	v_cvt_pk_bf16_f32 v87, v50, v51
	v_cvt_pk_bf16_f32 v88, v88, v89
	v_cvt_pk_bf16_f32 v89, v48, v49
	v_lshrrev_b32_e32 v48, 2, v0
	v_add_u32_e32 v48, 0x1a300, v48
	ds_read_b32 v48, v48 offset:4
	v_lshl_add_u64 v[46:47], v[46:47], 1, s[56:57]
	v_lshl_add_u64 v[46:47], v[158:159], 1, v[46:47]
	global_store_dwordx4 v[46:47], v[86:89], off
	s_waitcnt lgkmcnt(0)
	v_mov_b32_e32 v0, v48
	v_pk_mul_f32 v[48:49], v[42:43], v[0:1] op_sel_hi:[1,0]
	v_pk_mul_f32 v[42:43], v[44:45], v[0:1] op_sel_hi:[1,0]
	v_pk_mul_f32 v[44:45], v[58:59], v[48:49]
	v_pk_mul_f32 v[48:49], v[38:39], v[0:1] op_sel_hi:[1,0]
	v_pk_mul_f32 v[38:39], v[40:41], v[0:1] op_sel_hi:[1,0]
	v_pk_mul_f32 v[42:43], v[60:61], v[42:43]
	v_pk_mul_f32 v[38:39], v[56:57], v[38:39]
	v_pk_mul_f32 v[40:41], v[54:55], v[48:49]
	s_and_b64 vcc, exec, s[6:7]
	s_cbranch_vccnz .LBB0_342
	ds_bpermute_b32 v48, v172, v44
	ds_bpermute_b32 v49, v172, v45
	ds_bpermute_b32 v50, v172, v40
	ds_bpermute_b32 v52, v172, v42
	ds_bpermute_b32 v53, v172, v43
	ds_bpermute_b32 v51, v172, v41
	ds_bpermute_b32 v86, v172, v38
	ds_bpermute_b32 v87, v172, v39
	s_waitcnt lgkmcnt(6)
	v_pk_mul_f32 v[48:49], v[82:83], v[48:49]
	s_waitcnt lgkmcnt(3)
	v_pk_mul_f32 v[52:53], v[84:85], v[52:53]
	s_waitcnt vmcnt(2)
	v_pk_fma_f32 v[44:45], v[74:75], v[44:45], v[48:49]
	s_waitcnt lgkmcnt(2)
	v_pk_mul_f32 v[48:49], v[80:81], v[50:51]
	s_waitcnt lgkmcnt(0)
	v_pk_mul_f32 v[50:51], v[78:79], v[86:87]
	v_pk_fma_f32 v[42:43], v[76:77], v[42:43], v[52:53]
	s_waitcnt vmcnt(1)
	v_pk_fma_f32 v[38:39], v[72:73], v[38:39], v[50:51]
	v_pk_fma_f32 v[40:41], v[70:71], v[40:41], v[48:49]

.LBB0_345:
	v_lshlrev_b32_e32 v0, 5, v72
	v_add_u32_e32 v72, 0, v0
	v_add_u32_e32 v72, 0x20400, v72
	v_lshrrev_b32_e32 v72, 2, v72
	v_add_u32_e32 v72, 0x1a300, v72
	ds_read_b32 v72, v72
	s_waitcnt lgkmcnt(0)
	s_nop 0
	v_pk_mul_f32 v[74:75], v[34:35], v[72:73] op_sel_hi:[1,0]
	v_pk_mul_f32 v[34:35], v[36:37], v[72:73] op_sel_hi:[1,0]
	v_pk_mul_f32 v[30:31], v[30:31], v[72:73] op_sel_hi:[1,0]
	v_pk_mul_f32 v[32:33], v[32:33], v[72:73] op_sel_hi:[1,0]
	v_pk_mul_f32 v[34:35], v[68:69], v[34:35]
	v_pk_mul_f32 v[36:37], v[66:67], v[74:75]
	v_pk_mul_f32 v[32:33], v[64:65], v[32:33]
	s_and_b64 vcc, exec, s[6:7]
	v_pk_mul_f32 v[72:73], v[62:63], v[30:31]
	s_cbranch_vccnz .LBB0_347
	ds_bpermute_b32 v30, v172, v36
	ds_bpermute_b32 v31, v172, v37
	ds_bpermute_b32 v74, v172, v72
	ds_bpermute_b32 v76, v172, v34
	ds_bpermute_b32 v77, v172, v35
	ds_bpermute_b32 v75, v172, v73
	ds_bpermute_b32 v78, v172, v32
	ds_bpermute_b32 v79, v172, v33
	s_waitcnt lgkmcnt(6)
	v_pk_mul_f32 v[30:31], v[50:51], v[30:31]
	s_waitcnt lgkmcnt(3)
	v_pk_mul_f32 v[76:77], v[52:53], v[76:77]
	s_waitcnt vmcnt(1)
	v_pk_fma_f32 v[36:37], v[42:43], v[36:37], v[30:31]
	s_waitcnt lgkmcnt(2)
	v_pk_mul_f32 v[30:31], v[48:49], v[74:75]
	s_waitcnt lgkmcnt(0)
	v_pk_mul_f32 v[74:75], v[46:47], v[78:79]
	v_pk_fma_f32 v[34:35], v[44:45], v[34:35], v[76:77]
	s_waitcnt vmcnt(0)
	v_pk_fma_f32 v[32:33], v[40:41], v[32:33], v[74:75]
	v_pk_fma_f32 v[72:73], v[38:39], v[72:73], v[30:31]
.LBB0_347:
	v_mad_u64_u32 v[30:31], s[8:9], v70, s20, 0
	v_mov_b32_e32 v70, v31
	v_mad_u64_u32 v[70:71], s[8:9], v71, s20, v[70:71]
	v_add_u32_e32 v0, s33, v0
	v_mov_b32_e32 v31, v70
	v_cvt_pk_bf16_f32 v70, v36, v37
	v_cvt_pk_bf16_f32 v71, v34, v35
	v_cvt_pk_bf16_f32 v72, v72, v73
	v_cvt_pk_bf16_f32 v73, v32, v33
	v_lshrrev_b32_e32 v32, 2, v0
	v_add_u32_e32 v32, 0x1a300, v32
	ds_read_b32 v32, v32 offset:4
	v_lshl_add_u64 v[30:31], v[30:31], 1, s[56:57]
	v_lshl_add_u64 v[30:31], v[158:159], 1, v[30:31]
	global_store_dwordx4 v[30:31], v[70:73], off
	s_waitcnt lgkmcnt(0)
	v_mov_b32_e32 v0, v32
	v_pk_mul_f32 v[32:33], v[26:27], v[0:1] op_sel_hi:[1,0]
	v_pk_mul_f32 v[26:27], v[28:29], v[0:1] op_sel_hi:[1,0]
	v_pk_mul_f32 v[28:29], v[58:59], v[32:33]
	v_pk_mul_f32 v[32:33], v[22:23], v[0:1] op_sel_hi:[1,0]
	v_pk_mul_f32 v[22:23], v[24:25], v[0:1] op_sel_hi:[1,0]
	v_pk_mul_f32 v[26:27], v[60:61], v[26:27]
	v_pk_mul_f32 v[22:23], v[56:57], v[22:23]
	v_pk_mul_f32 v[24:25], v[54:55], v[32:33]
	s_and_b64 vcc, exec, s[6:7]
	s_cbranch_vccnz .LBB0_349
	ds_bpermute_b32 v32, v172, v28
	ds_bpermute_b32 v33, v172, v29
	ds_bpermute_b32 v34, v172, v24
	ds_bpermute_b32 v36, v172, v26
	ds_bpermute_b32 v37, v172, v27
	ds_bpermute_b32 v35, v172, v25
	ds_bpermute_b32 v70, v172, v22
	ds_bpermute_b32 v71, v172, v23
	s_waitcnt lgkmcnt(6)
	v_pk_mul_f32 v[32:33], v[50:51], v[32:33]
	s_waitcnt lgkmcnt(3)
	v_pk_mul_f32 v[36:37], v[52:53], v[36:37]
	s_waitcnt vmcnt(2)
	v_pk_fma_f32 v[28:29], v[42:43], v[28:29], v[32:33]
	s_waitcnt lgkmcnt(2)
	v_pk_mul_f32 v[32:33], v[48:49], v[34:35]
	s_waitcnt lgkmcnt(0)
	v_pk_mul_f32 v[34:35], v[46:47], v[70:71]
	v_pk_fma_f32 v[26:27], v[44:45], v[26:27], v[36:37]
	s_waitcnt vmcnt(1)
	v_pk_fma_f32 v[22:23], v[40:41], v[22:23], v[34:35]
	v_pk_fma_f32 v[24:25], v[38:39], v[24:25], v[32:33]

.LBB0_352:
	v_lshlrev_b32_e32 v0, 5, v40
	v_add_u32_e32 v40, 0, v0
	v_add_u32_e32 v40, 0x20400, v40
	v_lshrrev_b32_e32 v40, 2, v40
	v_add_u32_e32 v40, 0x1a300, v40
	ds_read_b32 v40, v40
	s_waitcnt lgkmcnt(0)
	s_nop 0
	v_pk_mul_f32 v[42:43], v[18:19], v[40:41] op_sel_hi:[1,0]
	v_pk_mul_f32 v[18:19], v[20:21], v[40:41] op_sel_hi:[1,0]
	v_pk_mul_f32 v[10:11], v[10:11], v[40:41] op_sel_hi:[1,0]
	v_pk_mul_f32 v[12:13], v[12:13], v[40:41] op_sel_hi:[1,0]
	v_pk_mul_f32 v[18:19], v[68:69], v[18:19]
	v_pk_mul_f32 v[20:21], v[66:67], v[42:43]
	v_pk_mul_f32 v[12:13], v[64:65], v[12:13]
	s_and_b64 vcc, exec, s[6:7]
	v_pk_mul_f32 v[40:41], v[62:63], v[10:11]
	s_cbranch_vccnz .LBB0_354
	ds_bpermute_b32 v10, v172, v20
	ds_bpermute_b32 v11, v172, v21
	ds_bpermute_b32 v42, v172, v40
	ds_bpermute_b32 v44, v172, v18
	ds_bpermute_b32 v45, v172, v19
	ds_bpermute_b32 v43, v172, v41
	ds_bpermute_b32 v46, v172, v12
	ds_bpermute_b32 v47, v172, v13
	s_waitcnt lgkmcnt(6)
	v_pk_mul_f32 v[10:11], v[34:35], v[10:11]
	s_waitcnt lgkmcnt(3)
	v_pk_mul_f32 v[44:45], v[36:37], v[44:45]
	s_waitcnt vmcnt(1)
	v_pk_fma_f32 v[20:21], v[26:27], v[20:21], v[10:11]
	s_waitcnt lgkmcnt(2)
	v_pk_mul_f32 v[10:11], v[32:33], v[42:43]
	s_waitcnt lgkmcnt(0)
	v_pk_mul_f32 v[42:43], v[30:31], v[46:47]
	v_pk_fma_f32 v[18:19], v[28:29], v[18:19], v[44:45]
	s_waitcnt vmcnt(0)
	v_pk_fma_f32 v[12:13], v[24:25], v[12:13], v[42:43]
	v_pk_fma_f32 v[40:41], v[22:23], v[40:41], v[10:11]
.LBB0_354:
	v_mad_u64_u32 v[10:11], s[4:5], v38, s20, 0
	v_mov_b32_e32 v38, v11
	v_mad_u64_u32 v[38:39], s[4:5], v39, s20, v[38:39]
	v_add_u32_e32 v0, s33, v0
	v_mov_b32_e32 v11, v38
	v_cvt_pk_bf16_f32 v38, v20, v21
	v_cvt_pk_bf16_f32 v39, v18, v19
	v_cvt_pk_bf16_f32 v40, v40, v41
	v_cvt_pk_bf16_f32 v41, v12, v13
	v_lshrrev_b32_e32 v18, 2, v0
	v_add_u32_e32 v18, 0x1a300, v18
	ds_read_b32 v18, v18 offset:4
	v_lshl_add_u64 v[10:11], v[10:11], 1, s[56:57]
	v_lshl_add_u64 v[10:11], v[158:159], 1, v[10:11]
	global_store_dwordx4 v[10:11], v[38:41], off
	s_waitcnt lgkmcnt(0)
	v_mov_b32_e32 v0, v18
	v_pk_mul_f32 v[12:13], v[6:7], v[0:1] op_sel_hi:[1,0]
	v_pk_mul_f32 v[6:7], v[8:9], v[0:1] op_sel_hi:[1,0]
	v_pk_mul_f32 v[8:9], v[58:59], v[12:13]
	v_pk_mul_f32 v[12:13], v[2:3], v[0:1] op_sel_hi:[1,0]
	v_pk_mul_f32 v[2:3], v[4:5], v[0:1] op_sel_hi:[1,0]
	v_pk_mul_f32 v[6:7], v[60:61], v[6:7]
	v_pk_mul_f32 v[2:3], v[56:57], v[2:3]
	v_pk_mul_f32 v[4:5], v[54:55], v[12:13]
	s_and_b64 vcc, exec, s[6:7]
	s_cbranch_vccnz .LBB0_356
	ds_bpermute_b32 v12, v172, v8
	ds_bpermute_b32 v13, v172, v9
	ds_bpermute_b32 v18, v172, v4
	ds_bpermute_b32 v20, v172, v6
	ds_bpermute_b32 v21, v172, v7
	ds_bpermute_b32 v19, v172, v5
	ds_bpermute_b32 v38, v172, v2
	ds_bpermute_b32 v39, v172, v3
	s_waitcnt lgkmcnt(6)
	v_pk_mul_f32 v[12:13], v[34:35], v[12:13]
	s_waitcnt lgkmcnt(3)
	v_pk_mul_f32 v[20:21], v[36:37], v[20:21]
	s_waitcnt vmcnt(2)
	v_pk_fma_f32 v[8:9], v[26:27], v[8:9], v[12:13]
	s_waitcnt lgkmcnt(2)
	v_pk_mul_f32 v[12:13], v[32:33], v[18:19]
	s_waitcnt lgkmcnt(0)
	v_pk_mul_f32 v[18:19], v[30:31], v[38:39]
	v_pk_fma_f32 v[6:7], v[28:29], v[6:7], v[20:21]
	s_waitcnt vmcnt(1)
	v_pk_fma_f32 v[2:3], v[24:25], v[2:3], v[18:19]
	v_pk_fma_f32 v[4:5], v[22:23], v[4:5], v[12:13]
